# P5 epilogue: leading half runs its first TWO row blocks before the align barrier
# baseline (speedup 1.0000x reference)
; __device__ __forceinline__ unsigned cvt_pk_bf16(float lo, float hi) { f32x2 v = {lo, hi}; return __builtin_bit_cast(unsigned, __builtin_convertvector(v, nbf16x2e)); }
; #define PG8_BAR __builtin_amdgcn_s_barrier()
; template <class Epi, class Sched, bool ALIGN_EPI = false, bool SP2 = false>
; __device__ __forceinline__ void gemm_phase(PG8_LAS unsigned char* lds, const Gemm g, const Sched& S, const Epi& E) {
;     ...
;         if constexpr (ALIGN_EPI) { if (wr == 0) PG8_BAR; }
;     __device__ __forceinline__ void operator()(const f32x4 (&acc)[2][2][4][2], const Unit& u, int wr, int wc, int fr, int fq) const {
;     ...
;                 float v[8];
; #pragma unroll
;                 for (int n = 0; n < 2; ++n)
; #pragma unroll
;                     for (int i = 0; i < 4; ++i) { const float g = acc[ai][0][m][n][i] * rs, up = acc[ai][1][m][n][i] * rs; v[4 * n + i] = g * __builtin_amdgcn_rcpf(1.0f + __expf(-g)) * up; }
;                 u32x4 w; w.x = cvt_pk_bf16(v[0], v[1]); w.y = cvt_pk_bf16(v[2], v[3]); w.z = cvt_pk_bf16(v[4], v[5]); w.w = cvt_pk_bf16(v[6], v[7]);
;                 *(u32x4*)(O + (size_t)row * 2816 + u.pn * HALF + wc * 32 + 8 * fq) = w;
.Lgu_fast:
	s_lshl_b32 s24, s24, 7
	s_ashr_i32 s25, s24, 31
	v_mov_b64_e32 v[236:237], s[34:35]
	v_mad_u64_u32 v[236:237], s[26:27], v148, s68, v[236:237]
	v_lshl_add_u64 v[236:237], s[24:25], 1, v[236:237]
	v_lshl_add_u64 v[236:237], v[236:237], 0, s[4:5]
	v_lshl_add_u64 v[236:237], v[236:237], 0, v[138:139]
	v_pk_mul_f32 v[126:127], v[126:127], v[228:229] op_sel_hi:[1,0]
	v_pk_mul_f32 v[128:129], v[128:129], v[228:229] op_sel_hi:[1,0]
	v_pk_mul_f32 v[122:123], v[122:123], v[228:229] op_sel_hi:[1,0]
	v_pk_mul_f32 v[124:125], v[124:125], v[228:229] op_sel_hi:[1,0]
	v_pk_mul_f32 v[176:177], v[126:127], v[184:185] op_sel_hi:[1,0]
	v_pk_mul_f32 v[178:179], v[128:129], v[184:185] op_sel_hi:[1,0]
	v_pk_mul_f32 v[180:181], v[122:123], v[184:185] op_sel_hi:[1,0]
	v_pk_mul_f32 v[182:183], v[124:125], v[184:185] op_sel_hi:[1,0]
	v_exp_f32_e32 v176, v176
	v_exp_f32_e32 v177, v177
	v_exp_f32_e32 v178, v178
	v_exp_f32_e32 v179, v179
	v_exp_f32_e32 v180, v180
	v_exp_f32_e32 v181, v181
	v_exp_f32_e32 v182, v182
	v_exp_f32_e32 v183, v183
	v_pk_add_f32 v[176:177], v[176:177], v[186:187] op_sel_hi:[1,0]
	v_pk_add_f32 v[178:179], v[178:179], v[186:187] op_sel_hi:[1,0]
	v_pk_add_f32 v[180:181], v[180:181], v[186:187] op_sel_hi:[1,0]
	v_pk_add_f32 v[182:183], v[182:183], v[186:187] op_sel_hi:[1,0]
	v_rcp_f32_e32 v176, v176
	v_rcp_f32_e32 v177, v177
	v_rcp_f32_e32 v178, v178
	v_rcp_f32_e32 v179, v179
	v_rcp_f32_e32 v180, v180
	v_rcp_f32_e32 v181, v181
	v_rcp_f32_e32 v182, v182
	v_rcp_f32_e32 v183, v183
	v_pk_mul_f32 v[118:119], v[118:119], v[228:229] op_sel_hi:[1,0]
	v_pk_mul_f32 v[120:121], v[120:121], v[228:229] op_sel_hi:[1,0]
	v_pk_mul_f32 v[114:115], v[114:115], v[228:229] op_sel_hi:[1,0]
	v_pk_mul_f32 v[116:117], v[116:117], v[228:229] op_sel_hi:[1,0]
	v_pk_mul_f32 v[126:127], v[126:127], v[176:177]
	v_pk_mul_f32 v[128:129], v[128:129], v[178:179]
	v_pk_mul_f32 v[122:123], v[122:123], v[180:181]
	v_pk_mul_f32 v[124:125], v[124:125], v[182:183]
	v_pk_mul_f32 v[118:119], v[118:119], v[126:127]
	v_pk_mul_f32 v[120:121], v[120:121], v[128:129]
	v_pk_mul_f32 v[122:123], v[114:115], v[122:123]
	v_pk_mul_f32 v[124:125], v[116:117], v[124:125]
	v_cvt_pk_bf16_f32 v114, v118, v119
	v_cvt_pk_bf16_f32 v115, v120, v121
	v_cvt_pk_bf16_f32 v116, v122, v123
	v_cvt_pk_bf16_f32 v117, v124, v125
	global_store_dwordx4 v[236:237], v[114:117], off
	v_mov_b32_e32 v188, v229
	v_pk_mul_f32 v[110:111], v[110:111], v[188:189] op_sel_hi:[1,0]
	v_pk_mul_f32 v[112:113], v[112:113], v[188:189] op_sel_hi:[1,0]
	v_pk_mul_f32 v[106:107], v[106:107], v[188:189] op_sel_hi:[1,0]
	v_pk_mul_f32 v[108:109], v[108:109], v[188:189] op_sel_hi:[1,0]
	v_pk_mul_f32 v[176:177], v[110:111], v[184:185] op_sel_hi:[1,0]
	v_pk_mul_f32 v[178:179], v[112:113], v[184:185] op_sel_hi:[1,0]
	v_pk_mul_f32 v[180:181], v[106:107], v[184:185] op_sel_hi:[1,0]
	v_pk_mul_f32 v[182:183], v[108:109], v[184:185] op_sel_hi:[1,0]
	v_exp_f32_e32 v176, v176
	v_exp_f32_e32 v177, v177
	v_exp_f32_e32 v178, v178
	v_exp_f32_e32 v179, v179
	v_exp_f32_e32 v180, v180
	v_exp_f32_e32 v181, v181
	v_exp_f32_e32 v182, v182
	v_exp_f32_e32 v183, v183
	v_pk_add_f32 v[176:177], v[176:177], v[186:187] op_sel_hi:[1,0]
	v_pk_add_f32 v[178:179], v[178:179], v[186:187] op_sel_hi:[1,0]
	v_pk_add_f32 v[180:181], v[180:181], v[186:187] op_sel_hi:[1,0]
	v_pk_add_f32 v[182:183], v[182:183], v[186:187] op_sel_hi:[1,0]
	v_rcp_f32_e32 v176, v176
	v_rcp_f32_e32 v177, v177
	v_rcp_f32_e32 v178, v178
	v_rcp_f32_e32 v179, v179
	v_rcp_f32_e32 v180, v180
	v_rcp_f32_e32 v181, v181
	v_rcp_f32_e32 v182, v182
	v_rcp_f32_e32 v183, v183
	v_pk_mul_f32 v[102:103], v[102:103], v[188:189] op_sel_hi:[1,0]
	v_pk_mul_f32 v[104:105], v[104:105], v[188:189] op_sel_hi:[1,0]
	v_pk_mul_f32 v[98:99], v[98:99], v[188:189] op_sel_hi:[1,0]
	v_pk_mul_f32 v[100:101], v[100:101], v[188:189] op_sel_hi:[1,0]
	v_pk_mul_f32 v[110:111], v[110:111], v[176:177]
	v_pk_mul_f32 v[112:113], v[112:113], v[178:179]
	v_pk_mul_f32 v[106:107], v[106:107], v[180:181]
	v_pk_mul_f32 v[108:109], v[108:109], v[182:183]
	v_pk_mul_f32 v[102:103], v[102:103], v[110:111]
	v_pk_mul_f32 v[104:105], v[104:105], v[112:113]
	v_pk_mul_f32 v[106:107], v[98:99], v[106:107]
	v_pk_mul_f32 v[108:109], v[100:101], v[108:109]
	v_cvt_pk_bf16_f32 v98, v102, v103
	v_cvt_pk_bf16_f32 v99, v104, v105
	v_cvt_pk_bf16_f32 v100, v106, v107
	v_cvt_pk_bf16_f32 v101, v108, v109
	v_lshl_add_u64 v[236:237], v[236:237], 0, s[100:101]
	global_store_dwordx4 v[236:237], v[98:101], off
	s_bitcmp1_b32 s14, 0
	s_cbranch_scc0 .Lgu_nb1
	s_barrier
; __device__ __forceinline__ unsigned cvt_pk_bf16(float lo, float hi) { f32x2 v = {lo, hi}; return __builtin_bit_cast(unsigned, __builtin_convertvector(v, nbf16x2e)); }
;     __device__ __forceinline__ void operator()(const f32x4 (&acc)[2][2][4][2], const Unit& u, int wr, int wc, int fr, int fq) const {
;     ...
;                 float v[8];
; #pragma unroll
;                 for (int n = 0; n < 2; ++n)
; #pragma unroll
;                     for (int i = 0; i < 4; ++i) { const float g = acc[ai][0][m][n][i] * rs, up = acc[ai][1][m][n][i] * rs; v[4 * n + i] = g * __builtin_amdgcn_rcpf(1.0f + __expf(-g)) * up; }
;                 u32x4 w; w.x = cvt_pk_bf16(v[0], v[1]); w.y = cvt_pk_bf16(v[2], v[3]); w.z = cvt_pk_bf16(v[4], v[5]); w.w = cvt_pk_bf16(v[6], v[7]);
;                 *(u32x4*)(O + (size_t)row * 2816 + u.pn * HALF + wc * 32 + 8 * fq) = w;
.Lgu_nb1:
	v_pk_mul_f32 v[94:95], v[94:95], v[230:231] op_sel_hi:[1,0]
	v_pk_mul_f32 v[96:97], v[96:97], v[230:231] op_sel_hi:[1,0]
	v_pk_mul_f32 v[90:91], v[90:91], v[230:231] op_sel_hi:[1,0]
	v_pk_mul_f32 v[92:93], v[92:93], v[230:231] op_sel_hi:[1,0]
	v_pk_mul_f32 v[176:177], v[94:95], v[184:185] op_sel_hi:[1,0]
	v_pk_mul_f32 v[178:179], v[96:97], v[184:185] op_sel_hi:[1,0]
	v_pk_mul_f32 v[180:181], v[90:91], v[184:185] op_sel_hi:[1,0]
	v_pk_mul_f32 v[182:183], v[92:93], v[184:185] op_sel_hi:[1,0]
	v_exp_f32_e32 v176, v176
	v_exp_f32_e32 v177, v177
	v_exp_f32_e32 v178, v178
	v_exp_f32_e32 v179, v179
	v_exp_f32_e32 v180, v180
	v_exp_f32_e32 v181, v181
	v_exp_f32_e32 v182, v182
	v_exp_f32_e32 v183, v183
	v_pk_add_f32 v[176:177], v[176:177], v[186:187] op_sel_hi:[1,0]
	v_pk_add_f32 v[178:179], v[178:179], v[186:187] op_sel_hi:[1,0]
	v_pk_add_f32 v[180:181], v[180:181], v[186:187] op_sel_hi:[1,0]
	v_pk_add_f32 v[182:183], v[182:183], v[186:187] op_sel_hi:[1,0]
	v_rcp_f32_e32 v176, v176
	v_rcp_f32_e32 v177, v177
	v_rcp_f32_e32 v178, v178
	v_rcp_f32_e32 v179, v179
	v_rcp_f32_e32 v180, v180
	v_rcp_f32_e32 v181, v181
	v_rcp_f32_e32 v182, v182
	v_rcp_f32_e32 v183, v183
	v_pk_mul_f32 v[86:87], v[86:87], v[230:231] op_sel_hi:[1,0]
	v_pk_mul_f32 v[88:89], v[88:89], v[230:231] op_sel_hi:[1,0]
	v_pk_mul_f32 v[82:83], v[82:83], v[230:231] op_sel_hi:[1,0]
	v_pk_mul_f32 v[84:85], v[84:85], v[230:231] op_sel_hi:[1,0]
	v_pk_mul_f32 v[94:95], v[94:95], v[176:177]
	v_pk_mul_f32 v[96:97], v[96:97], v[178:179]
	v_pk_mul_f32 v[90:91], v[90:91], v[180:181]
	v_pk_mul_f32 v[92:93], v[92:93], v[182:183]
	v_pk_mul_f32 v[86:87], v[86:87], v[94:95]
	v_pk_mul_f32 v[88:89], v[88:89], v[96:97]
	v_pk_mul_f32 v[90:91], v[82:83], v[90:91]
	v_pk_mul_f32 v[92:93], v[84:85], v[92:93]
	v_cvt_pk_bf16_f32 v82, v86, v87
	v_cvt_pk_bf16_f32 v83, v88, v89
	v_cvt_pk_bf16_f32 v84, v90, v91
	v_cvt_pk_bf16_f32 v85, v92, v93
	v_lshl_add_u64 v[236:237], v[236:237], 0, s[100:101]
	global_store_dwordx4 v[236:237], v[82:85], off
	v_mov_b32_e32 v188, v231
	v_pk_mul_f32 v[78:79], v[78:79], v[188:189] op_sel_hi:[1,0]
	v_pk_mul_f32 v[80:81], v[80:81], v[188:189] op_sel_hi:[1,0]
	v_pk_mul_f32 v[74:75], v[74:75], v[188:189] op_sel_hi:[1,0]
	v_pk_mul_f32 v[76:77], v[76:77], v[188:189] op_sel_hi:[1,0]
	v_pk_mul_f32 v[176:177], v[78:79], v[184:185] op_sel_hi:[1,0]
	v_pk_mul_f32 v[178:179], v[80:81], v[184:185] op_sel_hi:[1,0]
	v_pk_mul_f32 v[180:181], v[74:75], v[184:185] op_sel_hi:[1,0]
	v_pk_mul_f32 v[182:183], v[76:77], v[184:185] op_sel_hi:[1,0]
	v_exp_f32_e32 v176, v176
	v_exp_f32_e32 v177, v177
	v_exp_f32_e32 v178, v178
	v_exp_f32_e32 v179, v179
	v_exp_f32_e32 v180, v180
	v_exp_f32_e32 v181, v181
	v_exp_f32_e32 v182, v182
	v_exp_f32_e32 v183, v183
	v_pk_add_f32 v[176:177], v[176:177], v[186:187] op_sel_hi:[1,0]
	v_pk_add_f32 v[178:179], v[178:179], v[186:187] op_sel_hi:[1,0]
	v_pk_add_f32 v[180:181], v[180:181], v[186:187] op_sel_hi:[1,0]
	v_pk_add_f32 v[182:183], v[182:183], v[186:187] op_sel_hi:[1,0]
	v_rcp_f32_e32 v176, v176
	v_rcp_f32_e32 v177, v177
	v_rcp_f32_e32 v178, v178
	v_rcp_f32_e32 v179, v179
	v_rcp_f32_e32 v180, v180
	v_rcp_f32_e32 v181, v181
	v_rcp_f32_e32 v182, v182
	v_rcp_f32_e32 v183, v183
	v_pk_mul_f32 v[70:71], v[70:71], v[188:189] op_sel_hi:[1,0]
	v_pk_mul_f32 v[72:73], v[72:73], v[188:189] op_sel_hi:[1,0]
	v_pk_mul_f32 v[66:67], v[66:67], v[188:189] op_sel_hi:[1,0]
	v_pk_mul_f32 v[68:69], v[68:69], v[188:189] op_sel_hi:[1,0]
	v_pk_mul_f32 v[78:79], v[78:79], v[176:177]
	v_pk_mul_f32 v[80:81], v[80:81], v[178:179]
	v_pk_mul_f32 v[74:75], v[74:75], v[180:181]
	v_pk_mul_f32 v[76:77], v[76:77], v[182:183]
	v_pk_mul_f32 v[70:71], v[70:71], v[78:79]
	v_pk_mul_f32 v[72:73], v[72:73], v[80:81]
	v_pk_mul_f32 v[74:75], v[66:67], v[74:75]
	v_pk_mul_f32 v[76:77], v[68:69], v[76:77]
	v_cvt_pk_bf16_f32 v66, v70, v71
	v_cvt_pk_bf16_f32 v67, v72, v73
	v_cvt_pk_bf16_f32 v68, v74, v75
	v_cvt_pk_bf16_f32 v69, v76, v77
	v_lshl_add_u64 v[236:237], v[236:237], 0, s[100:101]
	global_store_dwordx4 v[236:237], v[66:69], off
	v_pk_mul_f32 v[62:63], v[62:63], v[232:233] op_sel_hi:[1,0]
	v_pk_mul_f32 v[64:65], v[64:65], v[232:233] op_sel_hi:[1,0]
	v_pk_mul_f32 v[58:59], v[58:59], v[232:233] op_sel_hi:[1,0]
	v_pk_mul_f32 v[60:61], v[60:61], v[232:233] op_sel_hi:[1,0]
	v_pk_mul_f32 v[176:177], v[62:63], v[184:185] op_sel_hi:[1,0]
	v_pk_mul_f32 v[178:179], v[64:65], v[184:185] op_sel_hi:[1,0]
	v_pk_mul_f32 v[180:181], v[58:59], v[184:185] op_sel_hi:[1,0]
	v_pk_mul_f32 v[182:183], v[60:61], v[184:185] op_sel_hi:[1,0]
	v_exp_f32_e32 v176, v176
	v_exp_f32_e32 v177, v177
	v_exp_f32_e32 v178, v178
	v_exp_f32_e32 v179, v179
	v_exp_f32_e32 v180, v180
	v_exp_f32_e32 v181, v181
	v_exp_f32_e32 v182, v182
	v_exp_f32_e32 v183, v183
	v_pk_add_f32 v[176:177], v[176:177], v[186:187] op_sel_hi:[1,0]
	v_pk_add_f32 v[178:179], v[178:179], v[186:187] op_sel_hi:[1,0]
	v_pk_add_f32 v[180:181], v[180:181], v[186:187] op_sel_hi:[1,0]
	v_pk_add_f32 v[182:183], v[182:183], v[186:187] op_sel_hi:[1,0]
	v_rcp_f32_e32 v176, v176
	v_rcp_f32_e32 v177, v177
	v_rcp_f32_e32 v178, v178
	v_rcp_f32_e32 v179, v179
	v_rcp_f32_e32 v180, v180
	v_rcp_f32_e32 v181, v181
	v_rcp_f32_e32 v182, v182
	v_rcp_f32_e32 v183, v183
	v_pk_mul_f32 v[54:55], v[54:55], v[232:233] op_sel_hi:[1,0]
	v_pk_mul_f32 v[56:57], v[56:57], v[232:233] op_sel_hi:[1,0]
	v_pk_mul_f32 v[50:51], v[50:51], v[232:233] op_sel_hi:[1,0]
	v_pk_mul_f32 v[52:53], v[52:53], v[232:233] op_sel_hi:[1,0]
	v_pk_mul_f32 v[62:63], v[62:63], v[176:177]
	v_pk_mul_f32 v[64:65], v[64:65], v[178:179]
	v_pk_mul_f32 v[58:59], v[58:59], v[180:181]
	v_pk_mul_f32 v[60:61], v[60:61], v[182:183]
; __device__ __forceinline__ unsigned cvt_pk_bf16(float lo, float hi) { f32x2 v = {lo, hi}; return __builtin_bit_cast(unsigned, __builtin_convertvector(v, nbf16x2e)); }
;     __device__ __forceinline__ void operator()(const f32x4 (&acc)[2][2][4][2], const Unit& u, int wr, int wc, int fr, int fq) const {
;     ...
;                 float v[8];
; #pragma unroll
;                 for (int n = 0; n < 2; ++n)
; #pragma unroll
;                     for (int i = 0; i < 4; ++i) { const float g = acc[ai][0][m][n][i] * rs, up = acc[ai][1][m][n][i] * rs; v[4 * n + i] = g * __builtin_amdgcn_rcpf(1.0f + __expf(-g)) * up; }
;                 u32x4 w; w.x = cvt_pk_bf16(v[0], v[1]); w.y = cvt_pk_bf16(v[2], v[3]); w.z = cvt_pk_bf16(v[4], v[5]); w.w = cvt_pk_bf16(v[6], v[7]);
;                 *(u32x4*)(O + (size_t)row * 2816 + u.pn * HALF + wc * 32 + 8 * fq) = w;
	v_pk_mul_f32 v[54:55], v[54:55], v[62:63]
	v_pk_mul_f32 v[56:57], v[56:57], v[64:65]
	v_pk_mul_f32 v[58:59], v[50:51], v[58:59]
	v_pk_mul_f32 v[60:61], v[52:53], v[60:61]
	v_cvt_pk_bf16_f32 v50, v54, v55
	v_cvt_pk_bf16_f32 v51, v56, v57
	v_cvt_pk_bf16_f32 v52, v58, v59
	v_cvt_pk_bf16_f32 v53, v60, v61
	v_lshl_add_u64 v[236:237], v[236:237], 0, s[98:99]
	global_store_dwordx4 v[236:237], v[50:53], off
	v_mov_b32_e32 v188, v233
	v_pk_mul_f32 v[46:47], v[46:47], v[188:189] op_sel_hi:[1,0]
	v_pk_mul_f32 v[48:49], v[48:49], v[188:189] op_sel_hi:[1,0]
	v_pk_mul_f32 v[42:43], v[42:43], v[188:189] op_sel_hi:[1,0]
	v_pk_mul_f32 v[44:45], v[44:45], v[188:189] op_sel_hi:[1,0]
	v_pk_mul_f32 v[176:177], v[46:47], v[184:185] op_sel_hi:[1,0]
	v_pk_mul_f32 v[178:179], v[48:49], v[184:185] op_sel_hi:[1,0]
	v_pk_mul_f32 v[180:181], v[42:43], v[184:185] op_sel_hi:[1,0]
	v_pk_mul_f32 v[182:183], v[44:45], v[184:185] op_sel_hi:[1,0]
	v_exp_f32_e32 v176, v176
	v_exp_f32_e32 v177, v177
	v_exp_f32_e32 v178, v178
	v_exp_f32_e32 v179, v179
	v_exp_f32_e32 v180, v180
	v_exp_f32_e32 v181, v181
	v_exp_f32_e32 v182, v182
	v_exp_f32_e32 v183, v183
	v_pk_add_f32 v[176:177], v[176:177], v[186:187] op_sel_hi:[1,0]
	v_pk_add_f32 v[178:179], v[178:179], v[186:187] op_sel_hi:[1,0]
	v_pk_add_f32 v[180:181], v[180:181], v[186:187] op_sel_hi:[1,0]
	v_pk_add_f32 v[182:183], v[182:183], v[186:187] op_sel_hi:[1,0]
	v_rcp_f32_e32 v176, v176
	v_rcp_f32_e32 v177, v177
	v_rcp_f32_e32 v178, v178
	v_rcp_f32_e32 v179, v179
	v_rcp_f32_e32 v180, v180
	v_rcp_f32_e32 v181, v181
	v_rcp_f32_e32 v182, v182
	v_rcp_f32_e32 v183, v183
	v_pk_mul_f32 v[38:39], v[38:39], v[188:189] op_sel_hi:[1,0]
	v_pk_mul_f32 v[40:41], v[40:41], v[188:189] op_sel_hi:[1,0]
	v_pk_mul_f32 v[34:35], v[34:35], v[188:189] op_sel_hi:[1,0]
	v_pk_mul_f32 v[36:37], v[36:37], v[188:189] op_sel_hi:[1,0]
	v_pk_mul_f32 v[46:47], v[46:47], v[176:177]
	v_pk_mul_f32 v[48:49], v[48:49], v[178:179]
	v_pk_mul_f32 v[42:43], v[42:43], v[180:181]
	v_pk_mul_f32 v[44:45], v[44:45], v[182:183]
	v_pk_mul_f32 v[38:39], v[38:39], v[46:47]
	v_pk_mul_f32 v[40:41], v[40:41], v[48:49]
	v_pk_mul_f32 v[42:43], v[34:35], v[42:43]
	v_pk_mul_f32 v[44:45], v[36:37], v[44:45]
	v_cvt_pk_bf16_f32 v34, v38, v39
	v_cvt_pk_bf16_f32 v35, v40, v41
	v_cvt_pk_bf16_f32 v36, v42, v43
	v_cvt_pk_bf16_f32 v37, v44, v45
	v_lshl_add_u64 v[236:237], v[236:237], 0, s[100:101]
	global_store_dwordx4 v[236:237], v[34:37], off
	v_pk_mul_f32 v[30:31], v[30:31], v[234:235] op_sel_hi:[1,0]
	v_pk_mul_f32 v[32:33], v[32:33], v[234:235] op_sel_hi:[1,0]
	v_pk_mul_f32 v[26:27], v[26:27], v[234:235] op_sel_hi:[1,0]
	v_pk_mul_f32 v[28:29], v[28:29], v[234:235] op_sel_hi:[1,0]
	v_pk_mul_f32 v[176:177], v[30:31], v[184:185] op_sel_hi:[1,0]
	v_pk_mul_f32 v[178:179], v[32:33], v[184:185] op_sel_hi:[1,0]
	v_pk_mul_f32 v[180:181], v[26:27], v[184:185] op_sel_hi:[1,0]
	v_pk_mul_f32 v[182:183], v[28:29], v[184:185] op_sel_hi:[1,0]
	v_exp_f32_e32 v176, v176
	v_exp_f32_e32 v177, v177
	v_exp_f32_e32 v178, v178
	v_exp_f32_e32 v179, v179
	v_exp_f32_e32 v180, v180
	v_exp_f32_e32 v181, v181
	v_exp_f32_e32 v182, v182
	v_exp_f32_e32 v183, v183
	v_pk_add_f32 v[176:177], v[176:177], v[186:187] op_sel_hi:[1,0]
	v_pk_add_f32 v[178:179], v[178:179], v[186:187] op_sel_hi:[1,0]
	v_pk_add_f32 v[180:181], v[180:181], v[186:187] op_sel_hi:[1,0]
	v_pk_add_f32 v[182:183], v[182:183], v[186:187] op_sel_hi:[1,0]
	v_rcp_f32_e32 v176, v176
	v_rcp_f32_e32 v177, v177
	v_rcp_f32_e32 v178, v178
	v_rcp_f32_e32 v179, v179
	v_rcp_f32_e32 v180, v180
	v_rcp_f32_e32 v181, v181
	v_rcp_f32_e32 v182, v182
	v_rcp_f32_e32 v183, v183
	v_pk_mul_f32 v[22:23], v[22:23], v[234:235] op_sel_hi:[1,0]
	v_pk_mul_f32 v[24:25], v[24:25], v[234:235] op_sel_hi:[1,0]
	v_pk_mul_f32 v[18:19], v[18:19], v[234:235] op_sel_hi:[1,0]
	v_pk_mul_f32 v[20:21], v[20:21], v[234:235] op_sel_hi:[1,0]
	v_pk_mul_f32 v[30:31], v[30:31], v[176:177]
	v_pk_mul_f32 v[32:33], v[32:33], v[178:179]
	v_pk_mul_f32 v[26:27], v[26:27], v[180:181]
	v_pk_mul_f32 v[28:29], v[28:29], v[182:183]
	v_pk_mul_f32 v[22:23], v[22:23], v[30:31]
	v_pk_mul_f32 v[24:25], v[24:25], v[32:33]
	v_pk_mul_f32 v[26:27], v[18:19], v[26:27]
	v_pk_mul_f32 v[28:29], v[20:21], v[28:29]
	v_cvt_pk_bf16_f32 v18, v22, v23
	v_cvt_pk_bf16_f32 v19, v24, v25
	v_cvt_pk_bf16_f32 v20, v26, v27
	v_cvt_pk_bf16_f32 v21, v28, v29
	v_lshl_add_u64 v[236:237], v[236:237], 0, s[100:101]
	global_store_dwordx4 v[236:237], v[18:21], off
	v_mov_b32_e32 v188, v235
	v_pk_mul_f32 v[14:15], v[14:15], v[188:189] op_sel_hi:[1,0]
	v_pk_mul_f32 v[16:17], v[16:17], v[188:189] op_sel_hi:[1,0]
	v_pk_mul_f32 v[10:11], v[10:11], v[188:189] op_sel_hi:[1,0]
	v_pk_mul_f32 v[12:13], v[12:13], v[188:189] op_sel_hi:[1,0]
	v_pk_mul_f32 v[176:177], v[14:15], v[184:185] op_sel_hi:[1,0]
	v_pk_mul_f32 v[178:179], v[16:17], v[184:185] op_sel_hi:[1,0]
	v_pk_mul_f32 v[180:181], v[10:11], v[184:185] op_sel_hi:[1,0]
	v_pk_mul_f32 v[182:183], v[12:13], v[184:185] op_sel_hi:[1,0]
	v_exp_f32_e32 v176, v176
	v_exp_f32_e32 v177, v177
	v_exp_f32_e32 v178, v178
	v_exp_f32_e32 v179, v179
	v_exp_f32_e32 v180, v180
	v_exp_f32_e32 v181, v181
	v_exp_f32_e32 v182, v182
	v_exp_f32_e32 v183, v183
	v_pk_add_f32 v[176:177], v[176:177], v[186:187] op_sel_hi:[1,0]
	v_pk_add_f32 v[178:179], v[178:179], v[186:187] op_sel_hi:[1,0]
	v_pk_add_f32 v[180:181], v[180:181], v[186:187] op_sel_hi:[1,0]
	v_pk_add_f32 v[182:183], v[182:183], v[186:187] op_sel_hi:[1,0]
	v_rcp_f32_e32 v176, v176
	v_rcp_f32_e32 v177, v177
	v_rcp_f32_e32 v178, v178
	v_rcp_f32_e32 v179, v179
	v_rcp_f32_e32 v180, v180
	v_rcp_f32_e32 v181, v181
	v_rcp_f32_e32 v182, v182
	v_rcp_f32_e32 v183, v183
	v_pk_mul_f32 v[6:7], v[6:7], v[188:189] op_sel_hi:[1,0]
	v_pk_mul_f32 v[8:9], v[8:9], v[188:189] op_sel_hi:[1,0]
	v_pk_mul_f32 v[2:3], v[2:3], v[188:189] op_sel_hi:[1,0]
	v_pk_mul_f32 v[4:5], v[4:5], v[188:189] op_sel_hi:[1,0]
	v_pk_mul_f32 v[14:15], v[14:15], v[176:177]
	v_pk_mul_f32 v[16:17], v[16:17], v[178:179]
	v_pk_mul_f32 v[10:11], v[10:11], v[180:181]
	v_pk_mul_f32 v[12:13], v[12:13], v[182:183]
	v_pk_mul_f32 v[6:7], v[6:7], v[14:15]
	v_pk_mul_f32 v[8:9], v[8:9], v[16:17]
	v_pk_mul_f32 v[10:11], v[2:3], v[10:11]
	v_pk_mul_f32 v[12:13], v[4:5], v[12:13]
	v_cvt_pk_bf16_f32 v2, v6, v7
	v_cvt_pk_bf16_f32 v3, v8, v9
	v_cvt_pk_bf16_f32 v4, v10, v11
	v_cvt_pk_bf16_f32 v5, v12, v13
	v_lshl_add_u64 v[236:237], v[236:237], 0, s[100:101]
	s_andn2_b64 vcc, exec, s[0:1]
	s_mov_b64 s[0:1], -1
	global_store_dwordx4 v[236:237], v[2:5], off
	s_branch .Lgu_done
